# v62 + attention: L2 warm-up loads for the next unit's first K/V tile and CL span issued from the current unit's tail
# baseline (speedup 1.0000x reference)
.LBB0_562:
	v_max3_f32 v32, v0, v23, v30
	v_max3_f32 v34, v2, v3, v33
	s_and_b32 s0, s15, 0x3fffffc0
	v_max3_f32 v32, v32, v28, v31
	v_max3_f32 v34, v34, v6, v7
	s_lshl_b32 s0, s0, 2
	v_max3_f32 v32, v32, v4, v5
	v_max3_f32 v34, v34, v24, v27
	s_add_i32 s85, s0, 0
	v_max3_f32 v32, v32, v26, v29
	v_max3_f32 v34, v34, v10, v11
	s_add_i32 s0, 0, 0x14800
	v_max3_f32 v32, v32, v8, v9
	v_max3_f32 v34, v34, v20, v21
	s_cmp_lg_u32 0, -1
	v_max3_f32 v32, v32, v22, v25
	v_max3_f32 v34, v34, v14, v15
	s_mov_b32 s15, 1
	v_max3_f32 v32, v32, v12, v13
	v_max3_f32 v34, v34, v16, v17
	s_mov_b32 s20, 0
	v_max3_f32 v32, v32, v18, v19
	v_lshl_add_u32 v214, v207, 2, s85
	v_max_f32_e32 v32, v32, v34
	s_nop 0
	v_mov_b32_e32 v34, v32
	s_nop 1
	v_permlane32_swap_b32_e32 v32, v34
	v_max_f32_e32 v32, v32, v34
	v_lshlrev_b32_e32 v34, 1, v48
	v_sub_f32_e32 v0, v0, v32
	v_sub_f32_e32 v30, v30, v32
	v_sub_f32_e32 v23, v23, v32
	v_sub_f32_e32 v33, v33, v32
	v_sub_f32_e32 v2, v2, v32
	v_sub_f32_e32 v28, v28, v32
	v_sub_f32_e32 v3, v3, v32
	v_sub_f32_e32 v31, v31, v32
	v_sub_f32_e32 v4, v4, v32
	v_sub_f32_e32 v26, v26, v32
	v_sub_f32_e32 v5, v5, v32
	v_sub_f32_e32 v29, v29, v32
	v_sub_f32_e32 v6, v6, v32
	v_sub_f32_e32 v24, v24, v32
	v_sub_f32_e32 v7, v7, v32
	v_sub_f32_e32 v27, v27, v32
	v_sub_f32_e32 v8, v8, v32
	v_sub_f32_e32 v22, v22, v32
	v_sub_f32_e32 v9, v9, v32
	v_sub_f32_e32 v25, v25, v32
	v_sub_f32_e32 v10, v10, v32
	v_sub_f32_e32 v20, v20, v32
	v_sub_f32_e32 v11, v11, v32
	v_sub_f32_e32 v21, v21, v32
	v_sub_f32_e32 v12, v12, v32
	v_sub_f32_e32 v18, v18, v32
	v_sub_f32_e32 v13, v13, v32
	v_sub_f32_e32 v19, v19, v32
	v_sub_f32_e32 v14, v14, v32
	v_sub_f32_e32 v16, v16, v32
	v_sub_f32_e32 v15, v15, v32
	v_sub_f32_e32 v17, v17, v32
	s_nop 0
	v_exp_f32_e32 v96, v0
	v_add_u32_e32 v0, s0, v217
	v_sub_f32_e64 v219, -v1, v32
	v_exp_f32_e32 v97, v23
	v_exp_f32_e32 v98, v2
	v_exp_f32_e32 v99, v3
	v_exp_f32_e32 v100, v4
	v_exp_f32_e32 v101, v5
	v_exp_f32_e32 v102, v6
	v_exp_f32_e32 v103, v7
	v_exp_f32_e32 v104, v8
	v_exp_f32_e32 v105, v9
	v_exp_f32_e32 v106, v10
	v_exp_f32_e32 v107, v11
	v_exp_f32_e32 v108, v12
	v_exp_f32_e32 v109, v13
	v_exp_f32_e32 v110, v14
	v_exp_f32_e32 v111, v15
	v_exp_f32_e32 v80, v30
	v_exp_f32_e32 v81, v33
	v_exp_f32_e32 v82, v28
	v_exp_f32_e32 v83, v31
	v_exp_f32_e32 v84, v26
	v_exp_f32_e32 v85, v29
	v_exp_f32_e32 v86, v24
	v_exp_f32_e32 v87, v27
	v_exp_f32_e32 v88, v22
	v_exp_f32_e32 v89, v25
	v_exp_f32_e32 v90, v20
	v_exp_f32_e32 v91, v21
	v_exp_f32_e32 v92, v18
	v_exp_f32_e32 v93, v19
	v_exp_f32_e32 v94, v16
	v_exp_f32_e32 v95, v17
	ds_read_b128 v[2:5], v0 offset:256
	ds_read_b128 v[6:9], v0 offset:288
	ds_read_b128 v[10:13], v0 offset:320
	ds_read_b128 v[14:17], v0 offset:352
	ds_read_b128 v[18:21], v0 offset:384
	ds_read_b128 v[22:25], v0 offset:416
	ds_read_b128 v[26:29], v0 offset:448
	ds_read_b128 v[30:33], v0 offset:480
	s_waitcnt vmcnt(0) lgkmcnt(0)
	s_barrier
	s_cselect_b32 s63, 1, 0
	v_readfirstlane_b32 s60, v196
	s_cmp_lt_u32 s60, 64
	s_cbranch_scc0 .Lmy_kw_nopub
	v_readfirstlane_b32 s60, v210
	s_min_u32 s61, s60, 0x3ff
	s_lshr_b32 s61, s61, 6
	s_lshl_b32 s61, s61, 2
	s_add_i32 s61, s61, 0x26840
	v_mov_b32_e32 v35, s61
	ds_read_b32 v37, v35
	v_mov_b32_e32 v36, s60
	v_mov_b32_e32 v35, 0x27f00
	s_waitcnt lgkmcnt(0)
	ds_write_b64 v35, v[36:37]
.Lmy_kw_nopub:
	s_cmp_lg_u32 s63, 0
	s_waitcnt lgkmcnt(7)
	v_sub_f32_e32 v65, v219, v3
	v_sub_f32_e32 v64, v219, v2
	v_lshl_add_u64 v[2:3], v[198:199], 0, s[40:41]
	s_mov_b32 s0, m0
	s_mov_b32 m0, s83
	s_nop 0
	global_load_lds_dwordx4 v[2:3], off
	s_mov_b32 m0, s0
	s_cselect_b32 s0, 0, 0
	s_add_i32 s0, s0, s14
	v_lshl_add_u64 v[2:3], v[200:201], 0, s[22:23]
	s_add_i32 s0, s0, 0x8000
	s_mov_b32 s1, m0
	s_mov_b32 m0, s0
	s_nop 0
	global_load_lds_dwordx4 v[2:3], off
	s_mov_b32 m0, s1
	ds_read_b128 v[172:175], v216 offset:8192
	ds_read_b128 v[168:171], v216 offset:8704
	ds_read_b128 v[164:167], v216 offset:10240
	ds_read_b128 v[160:163], v216 offset:10752
	ds_read_b128 v[156:159], v216 offset:12288
	ds_read_b128 v[152:155], v216 offset:12800
	ds_read_b128 v[148:151], v216 offset:14336
	ds_read_b128 v[144:147], v216 offset:14848
	v_and_b32_e32 v213, 32, v34
	v_lshlrev_b32_e32 v34, 4, v48
	v_and_b32_e32 v34, 0xc0, v34
	s_waitcnt vmcnt(2) lgkmcnt(0)
	s_barrier
	v_mov_b32_e32 v35, 0x27f00
	ds_read_b64 v[36:37], v35
	s_waitcnt lgkmcnt(0)
	v_readfirstlane_b32 s60, v36
	v_readfirstlane_b32 s61, v37
	s_min_u32 s60, s60, 0x3ff
	s_not_b32 s62, s60
	s_lshl_b32 s62, s62, 2
	s_and_b32 s62, s62, 0xfc
	s_lshl_b32 s63, s61, 10
	s_add_u32 s64, s74, s63
	s_addc_u32 s65, s75, 0
	v_lshlrev_b32_e32 v247, 2, v206
	v_xad_u32 v247, v247, -1, s62
	v_lshlrev_b32_e32 v38, 2, v247
	v_max_i32_e32 v39, 0, v38
	global_load_dword v243, v39, s[64:65]
	v_add_u32_e32 v39, -4, v38
	v_max_i32_e32 v39, 0, v39
	global_load_dword v244, v39, s[64:65]
	v_add_u32_e32 v39, -8, v38
	v_max_i32_e32 v39, 0, v39
	global_load_dword v245, v39, s[64:65]
	v_add_u32_e32 v39, -12, v38
	v_max_i32_e32 v39, 0, v39
	global_load_dword v246, v39, s[64:65]
	v_mov_b32_e32 v248, s62
	v_mov_b32_e32 v249, s61
	v_lshl_or_b32 v212, v208, 8, v34
	v_add_u32_e32 v34, 0, v213
	v_add3_u32 v218, v34, v209, v212
	s_waitcnt lgkmcnt(12)
	v_sub_f32_e32 v79, v219, v17
	v_sub_f32_e32 v78, v219, v16
	v_sub_f32_e32 v77, v219, v15
	v_sub_f32_e32 v76, v219, v14
	v_sub_f32_e32 v75, v219, v13
	v_sub_f32_e32 v74, v219, v12
	v_sub_f32_e32 v73, v219, v11
	v_sub_f32_e32 v72, v219, v10
	v_sub_f32_e32 v71, v219, v9
	v_sub_f32_e32 v70, v219, v8
	v_sub_f32_e32 v69, v219, v7
	v_sub_f32_e32 v68, v219, v6
	v_sub_f32_e32 v67, v219, v5
	v_sub_f32_e32 v66, v219, v4
	s_waitcnt lgkmcnt(8)
	v_sub_f32_e32 v63, v219, v33
	v_sub_f32_e32 v62, v219, v32
	v_sub_f32_e32 v61, v219, v31
	v_sub_f32_e32 v60, v219, v30
	v_sub_f32_e32 v59, v219, v29
	v_sub_f32_e32 v58, v219, v28
	v_sub_f32_e32 v57, v219, v27
	v_sub_f32_e32 v56, v219, v26
	v_sub_f32_e32 v55, v219, v25
	v_sub_f32_e32 v54, v219, v24
	v_sub_f32_e32 v53, v219, v23
	v_sub_f32_e32 v52, v219, v22
	v_sub_f32_e32 v51, v219, v21
	v_sub_f32_e32 v50, v219, v20
	v_sub_f32_e32 v49, v219, v19
	v_sub_f32_e32 v48, v219, v18
	s_cmp_lt_i32 s86, 7
	v_cmp_gt_u32_e64 s[0:1], 32, v206
	s_cbranch_scc1 .LBB0_578
	v_mov_b32_e32 v14, v1
	v_mov_b32_e32 v15, v1
	v_mov_b32_e32 v0, v1
	v_mov_b32_e32 v2, v1
	v_mov_b32_e32 v3, v1
	v_mov_b32_e32 v4, v1
	v_mov_b32_e32 v5, v1
	v_mov_b32_e32 v6, v1
	v_mov_b32_e32 v7, v1
	v_mov_b32_e32 v8, v1
	v_mov_b32_e32 v9, v1
	v_mov_b32_e32 v10, v1
	v_mov_b32_e32 v11, v1
	v_mov_b32_e32 v12, v1
	v_mov_b32_e32 v13, v1
	v_mov_b64_e32 v[46:47], v[14:15]
	v_mov_b64_e32 v[30:31], v[14:15]
	v_add_u32_e32 v188, s71, v217
	v_lshl_add_u64 v[184:185], v[200:201], 0, s[40:41]
	v_lshl_add_u64 v[186:187], v[198:199], 0, s[50:51]
	s_mov_b32 s15, 0
	s_movk_i32 s20, 0x4000
	s_movk_i32 s14, 0x2000
	v_mov_b32_e32 v220, 0
	s_mov_b32 s57, 6
	v_mov_b64_e32 v[44:45], v[12:13]
	v_mov_b64_e32 v[42:43], v[10:11]
	v_mov_b64_e32 v[40:41], v[8:9]
	v_mov_b64_e32 v[38:39], v[6:7]
	v_mov_b64_e32 v[36:37], v[4:5]
	v_mov_b64_e32 v[34:35], v[2:3]
	v_mov_b64_e32 v[32:33], v[0:1]
	v_mov_b64_e32 v[28:29], v[12:13]
	v_mov_b64_e32 v[26:27], v[10:11]
	v_mov_b64_e32 v[24:25], v[8:9]
	v_mov_b64_e32 v[22:23], v[6:7]
	v_mov_b64_e32 v[20:21], v[4:5]
	v_mov_b64_e32 v[18:19], v[2:3]
	v_mov_b64_e32 v[16:17], v[0:1]

.LBB0_650:
	v_readfirstlane_b32 s62, v248
	v_readfirstlane_b32 s61, v249
	v_cmp_lt_i32_e32 vcc, -1, v247
	s_nop 1
	v_cndmask_b32_e32 v100, 0, v243, vcc
	v_cmp_lt_i32_e32 vcc, 0, v247
	s_nop 1
	v_cndmask_b32_e32 v101, 0, v244, vcc
	v_cmp_lt_i32_e32 vcc, 1, v247
	s_nop 1
	v_cndmask_b32_e32 v102, 0, v245, vcc
	v_cmp_lt_i32_e32 vcc, 2, v247
	s_nop 1
	v_cndmask_b32_e32 v103, 0, v246, vcc
	v_add_f32_e32 v104, v100, v101
	v_add_f32_e32 v105, v104, v102
	v_add_f32_e32 v106, v105, v103
	v_mov_b32_e32 v107, v106
	s_nop 1
	v_add_f32_dpp v107, v107, v107 row_shr:1 row_mask:0xf bank_mask:0xf
	s_nop 1
	v_add_f32_dpp v107, v107, v107 row_shr:2 row_mask:0xf bank_mask:0xf
	s_nop 1
	v_add_f32_dpp v107, v107, v107 row_shr:4 row_mask:0xf bank_mask:0xf
	s_nop 1
	v_add_f32_dpp v107, v107, v107 row_shr:8 row_mask:0xf bank_mask:0xf
	s_nop 1
	v_add_f32_dpp v107, v107, v107 row_bcast:15 row_mask:0xa bank_mask:0xf
	s_nop 1
	v_add_f32_dpp v107, v107, v107 row_bcast:31 row_mask:0xc bank_mask:0xf
	s_nop 0
	v_sub_f32_e32 v108, v107, v106
	v_cmp_ge_f32_e64 s[64:65], v108, -v197
	v_cmp_lt_i32_e64 s[66:67], -1, v247
	s_and_b64 s[64:65], s[64:65], s[66:67]
	s_bcnt1_i32_b64 s63, s[64:65]
	v_add_f32_e32 v109, v108, v100
	v_cmp_ge_f32_e64 s[64:65], v109, -v197
	v_cmp_lt_i32_e64 s[66:67], 0, v247
	s_and_b64 s[64:65], s[64:65], s[66:67]
	s_bcnt1_i32_b64 s60, s[64:65]
	s_add_i32 s63, s63, s60
	v_add_f32_e32 v109, v108, v104
	v_cmp_ge_f32_e64 s[64:65], v109, -v197
	v_cmp_lt_i32_e64 s[66:67], 1, v247
	s_and_b64 s[64:65], s[64:65], s[66:67]
	s_bcnt1_i32_b64 s60, s[64:65]
	s_add_i32 s63, s63, s60
	v_add_f32_e32 v109, v108, v105
	v_cmp_ge_f32_e64 s[64:65], v109, -v197
	v_cmp_lt_i32_e64 s[66:67], 2, v247
	s_and_b64 s[64:65], s[64:65], s[66:67]
	s_bcnt1_i32_b64 s60, s[64:65]
	s_add_i32 s63, s63, s60
	s_sub_i32 s63, s62, s63
	s_and_b32 s63, s63, -2
	s_max_i32 s63, s63, 0
	s_lshl_b32 s60, s61, 7
	s_mov_b32 s64, s63
	s_mov_b32 s65, 0
	s_lshl_b64 s[64:65], s[64:65], 17
	s_add_u32 s64, s64, s60
	s_addc_u32 s65, s65, 0
	s_add_u32 s66, s44, s64
	s_addc_u32 s67, s45, s65
	v_lshlrev_b32_e32 v110, 11, v206
	global_load_dword v250, v110, s[66:67]
	s_add_u32 s66, s46, s64
	s_addc_u32 s67, s47, s65
	global_load_dword v251, v110, s[66:67]
	s_lshl_b32 s60, s61, 16
	s_lshl_b32 s64, s63, 8
	s_add_u32 s60, s60, s64
	s_add_u32 s66, s38, s60
	s_addc_u32 s67, s39, 0
	v_lshlrev_b32_e32 v111, 7, v206
	global_load_dword v252, v111, s[66:67]
	v_add_f32_e32 v0, v64, v65
	v_add_f32_e32 v0, v66, v0
	v_add_f32_e32 v0, v67, v0
	v_add_f32_e32 v0, v68, v0
	v_add_f32_e32 v0, v69, v0
	v_add_f32_e32 v0, v70, v0
	v_add_f32_e32 v0, v71, v0
	v_add_f32_e32 v0, v72, v0
	v_add_f32_e32 v0, v73, v0
	v_add_f32_e32 v0, v74, v0
	v_add_f32_e32 v0, v75, v0
	v_add_f32_e32 v0, v76, v0
	v_add_f32_e32 v0, v77, v0
	v_add_f32_e32 v0, v78, v0
	v_add_f32_e32 v0, v79, v0
	v_add_f32_e32 v0, v48, v0
	v_add_f32_e32 v0, v49, v0
	v_add_f32_e32 v0, v50, v0
	v_add_f32_e32 v0, v51, v0
	v_add_f32_e32 v0, v52, v0
	v_add_f32_e32 v0, v53, v0
	v_add_f32_e32 v0, v54, v0
	v_add_f32_e32 v0, v55, v0
	v_add_f32_e32 v0, v56, v0
	v_add_f32_e32 v0, v57, v0
	v_add_f32_e32 v0, v58, v0
	v_add_f32_e32 v0, v59, v0
	v_add_f32_e32 v0, v60, v0
	s_lshl_b64 s[16:17], s[10:11], 10
	v_add_f32_e32 v0, v61, v0
	s_cmp_lg_u32 0, -1
	v_add_f32_e32 v0, v62, v0
	s_cselect_b32 s10, 0, 0
	v_add_f32_e32 v0, v63, v0
	s_addk_i32 s10, 0x6000
	v_add_f32_e32 v0, v93, v0
	v_cvt_pk_bf16_f32 v48, v48, v49
	v_add3_u32 v95, v213, s10, v209
	v_cvt_pk_bf16_f32 v64, v64, v65
	v_cvt_pk_bf16_f32 v65, v66, v67
	v_cvt_pk_bf16_f32 v66, v68, v69
	v_cvt_pk_bf16_f32 v67, v70, v71
	v_cvt_pk_bf16_f32 v68, v72, v73
	v_cvt_pk_bf16_f32 v69, v74, v75
	v_cvt_pk_bf16_f32 v70, v76, v77
	v_cvt_pk_bf16_f32 v71, v78, v79
	v_cvt_pk_bf16_f32 v49, v50, v51
	v_cvt_pk_bf16_f32 v50, v52, v53
	v_cvt_pk_bf16_f32 v51, v54, v55
	v_cvt_pk_bf16_f32 v52, v56, v57
	v_cvt_pk_bf16_f32 v53, v58, v59
	v_cvt_pk_bf16_f32 v54, v60, v61
	v_cvt_pk_bf16_f32 v55, v62, v63
	v_add3_u32 v93, v95, v212, s87
	ds_read_b64_tr_b16 v[56:57],v93 offset:0
	ds_read_b64_tr_b16 v[58:59],v93 offset:512
	ds_read_b64_tr_b16 v[60:61],v93 offset:1024
	ds_read_b64_tr_b16 v[62:63],v93 offset:1536
	ds_read_b64_tr_b16 v[72:73],v93 offset:2048
	ds_read_b64_tr_b16 v[74:75],v93 offset:2560
	ds_read_b64_tr_b16 v[76:77],v93 offset:3072
	ds_read_b64_tr_b16 v[78:79],v93 offset:3584
	s_waitcnt lgkmcnt(0)
	s_nop 0
	v_mfma_f32_32x32x16_bf16 v[32:47], v[64:67], v[56:59], v[32:47]
	ds_read_b64_tr_b16 v[56:57],v93 offset:4096
	ds_read_b64_tr_b16 v[58:59],v93 offset:4608
	v_mfma_f32_32x32x16_bf16 v[32:47], v[68:71], v[60:63], v[32:47]
	ds_read_b64_tr_b16 v[60:61],v93 offset:5120
	ds_read_b64_tr_b16 v[62:63],v93 offset:5632
	v_mfma_f32_32x32x16_bf16 v[32:47], v[48:51], v[72:75], v[32:47]
	ds_read_b64_tr_b16 v[72:73],v93 offset:6144
	ds_read_b64_tr_b16 v[74:75],v93 offset:6656
	ds_read_b64_tr_b16 v[96:97],v93 offset:7168
	ds_read_b64_tr_b16 v[98:99],v93 offset:7680
	s_waitcnt lgkmcnt(0)
	v_mfma_f32_32x32x16_bf16 v[32:47], v[52:55], v[76:79], v[32:47]
	v_mfma_f32_32x32x16_bf16 v[16:31], v[64:67], v[56:59], v[16:31]
	v_cmp_gt_u32_e64 s[10:11], 32, v206
	v_mfma_f32_32x32x16_bf16 v[16:31], v[68:71], v[60:63], v[16:31]
	v_mfma_f32_32x32x16_bf16 v[16:31], v[48:51], v[72:75], v[16:31]
	v_mov_b32_e32 v48, v0
	s_nop 1
	v_permlane32_swap_b32_e32 v0, v48
	v_mfma_f32_32x32x16_bf16 v[16:31], v[52:55], v[96:99], v[16:31]
	s_and_saveexec_b64 s[60:61], s[10:11]
	v_add_f32_e32 v0, v0, v48
	ds_write_b32 v214, v0 offset:49280
	s_or_b64 exec, exec, s[60:61]
	s_waitcnt lgkmcnt(0)
	ds_read_b128 v[48:51], v94 offset:49280
	ds_read_b128 v[52:55], v94 offset:49312
	s_lshl_b64 s[16:17], s[16:17], 1
	s_add_u32 s16, s28, s16
	s_addc_u32 s17, s29, s17
	s_waitcnt lgkmcnt(1)
	v_rcp_f32_e32 v0, v48
	v_rcp_f32_e32 v56, v49
	s_add_u32 s12, s16, s12
	s_addc_u32 s13, s17, s13
	s_lshl_b32 s16, s78, 12
	s_add_i32 s16, s16, 0
	v_lshlrev_b32_e32 v63, 1, v207
	v_lshlrev_b32_e32 v64, 9, v208
	v_mul_f32_e32 v32, v32, v0
	v_mul_f32_e32 v0, v16, v0
	v_add3_u32 v63, s16, v63, v64
	v_cvt_pk_bf16_f32 v0, v0, s0
	v_rcp_f32_e32 v57, v50
	v_rcp_f32_e32 v58, v51
	s_waitcnt lgkmcnt(0)
	v_rcp_f32_e32 v59, v52
	ds_read_b128 v[48:51], v94 offset:49344
	v_rcp_f32_e32 v60, v53
	v_rcp_f32_e32 v61, v54
	v_rcp_f32_e32 v62, v55
	ds_read_b128 v[52:55], v94 offset:49376
	ds_write_b16 v63, v0 offset:51264
	v_mul_f32_e32 v0, v33, v56
	v_cvt_pk_bf16_f32 v0, v0, s0
	ds_write_b16 v63, v0 offset:51328
	v_mul_f32_e32 v0, v17, v56
	v_cvt_pk_bf16_f32 v0, v0, s0
	ds_write_b16 v63, v0 offset:51392
	v_mul_f32_e32 v0, v34, v57
	v_cvt_pk_bf16_f32 v0, v0, s0
	ds_write_b16 v63, v0 offset:51456
	v_mul_f32_e32 v0, v18, v57
	v_cvt_pk_bf16_f32 v0, v0, s0
	ds_write_b16 v63, v0 offset:51520
	v_mul_f32_e32 v0, v35, v58
	v_cvt_pk_bf16_f32 v0, v0, s0
	ds_write_b16 v63, v0 offset:51584
	v_mul_f32_e32 v0, v19, v58
	v_cvt_pk_bf16_f32 v0, v0, s0
	ds_write_b16 v63, v0 offset:51648
	v_mul_f32_e32 v0, v36, v59
	v_cvt_pk_bf16_f32 v0, v0, s0
	ds_write_b16 v63, v0 offset:52224
	v_mul_f32_e32 v0, v20, v59
	v_cvt_pk_bf16_f32 v0, v0, s0
	ds_write_b16 v63, v0 offset:52288
	v_mul_f32_e32 v0, v37, v60
	v_cvt_pk_bf16_f32 v0, v0, s0
	ds_write_b16 v63, v0 offset:52352
	v_mul_f32_e32 v0, v21, v60
	v_cvt_pk_bf16_f32 v0, v0, s0
	ds_write_b16 v63, v0 offset:52416
	v_mul_f32_e32 v0, v38, v61
	v_cvt_pk_bf16_f32 v0, v0, s0
	ds_write_b16 v63, v0 offset:52480
	v_mul_f32_e32 v0, v22, v61
	v_cvt_pk_bf16_f32 v0, v0, s0
	s_waitcnt lgkmcnt(13)
	v_rcp_f32_e32 v48, v48
	ds_write_b16 v63, v0 offset:52544
	v_mul_f32_e32 v0, v39, v62
	v_cvt_pk_bf16_f32 v0, v0, s0
	ds_write_b16 v63, v0 offset:52608
	v_mul_f32_e32 v0, v23, v62
	v_cvt_pk_bf16_f32 v0, v0, s0
	v_rcp_f32_e32 v49, v49
	ds_write_b16 v63, v0 offset:52672
	v_mul_f32_e32 v0, v40, v48
	v_cvt_pk_bf16_f32 v0, v0, s0
	ds_write_b16 v63, v0 offset:53248
	v_mul_f32_e32 v0, v24, v48
	v_cvt_pk_bf16_f32 v0, v0, s0
	v_rcp_f32_e32 v50, v50
	ds_write_b16 v63, v0 offset:53312
	v_mul_f32_e32 v0, v41, v49
	v_cvt_pk_bf16_f32 v0, v0, s0
	ds_write_b16 v63, v0 offset:53376
	v_mul_f32_e32 v0, v25, v49
	v_cvt_pk_bf16_f32 v0, v0, s0
	v_rcp_f32_e32 v51, v51
	ds_write_b16 v63, v0 offset:53440
	v_mul_f32_e32 v0, v42, v50
	v_cvt_pk_bf16_f32 v0, v0, s0
	ds_write_b16 v63, v0 offset:53504
	v_mul_f32_e32 v0, v26, v50
	v_cvt_pk_bf16_f32 v0, v0, s0
	s_waitcnt lgkmcnt(14)
	v_rcp_f32_e32 v52, v52
	ds_write_b16 v63, v0 offset:53568
	v_mul_f32_e32 v0, v43, v51
	v_cvt_pk_bf16_f32 v0, v0, s0
	ds_write_b16 v63, v0 offset:53632
	v_mul_f32_e32 v0, v27, v51
	v_cvt_pk_bf16_f32 v0, v0, s0
	v_rcp_f32_e32 v53, v53
	ds_write_b16 v63, v0 offset:53696
	v_mul_f32_e32 v0, v44, v52
	v_cvt_pk_bf16_f32 v0, v0, s0
	ds_write_b16 v63, v0 offset:54272
	v_mul_f32_e32 v0, v28, v52
	v_cvt_pk_bf16_f32 v0, v0, s0
	v_rcp_f32_e32 v54, v54
	ds_write_b16 v63, v0 offset:54336
	v_mul_f32_e32 v0, v45, v53
	v_cvt_pk_bf16_f32 v0, v0, s0
	ds_write_b16 v63, v0 offset:54400
	v_mul_f32_e32 v0, v29, v53
	v_cvt_pk_bf16_f32 v0, v0, s0
	v_rcp_f32_e32 v55, v55
	ds_write_b16 v63, v0 offset:54464
	v_mul_f32_e32 v0, v46, v54
	v_cvt_pk_bf16_f32 v0, v0, s0
	ds_write_b16 v63, v0 offset:54528
	v_mul_f32_e32 v0, v30, v54
	v_cvt_pk_bf16_f32 v0, v0, s0
	ds_write_b16 v63, v0 offset:54592
	v_mul_f32_e32 v0, v47, v55
	v_cvt_pk_bf16_f32 v0, v0, s0
	ds_write_b16 v63, v0 offset:54656
	v_mul_f32_e32 v0, v31, v55
	v_cvt_pk_bf16_f32 v32, v32, s0
	v_cvt_pk_bf16_f32 v0, v0, s0
	ds_write_b16 v63, v32 offset:51200
	ds_write_b16 v63, v0 offset:54720
	v_lshlrev_b32_e32 v0, 7, v14
	v_lshlrev_b32_e32 v14, 1, v90
	s_waitcnt lgkmcnt(0)
	v_add3_u32 v0, s16, v0, v14
	ds_read_b128 v[16:19], v0 offset:51200
	ds_read_b128 v[20:23], v0 offset:52224
	s_waitcnt vmcnt(6)
	v_lshlrev_b32_e32 v28, 16, v80
	v_and_b32_e32 v29, 0xffff0000, v80
	v_lshl_add_u64 v[24:25], v[88:89], 1, s[12:13]
	s_waitcnt lgkmcnt(1)
	v_lshlrev_b32_e32 v26, 16, v16
	v_and_b32_e32 v27, 0xffff0000, v16
	v_pk_mul_f32 v[26:27], v[28:29], v[26:27]
	v_lshlrev_b32_e32 v28, 16, v81
	v_cvt_pk_bf16_f32 v16, v26, v27
	v_lshlrev_b32_e32 v26, 16, v17
	v_and_b32_e32 v27, 0xffff0000, v17
	v_and_b32_e32 v29, 0xffff0000, v81
	v_pk_mul_f32 v[26:27], v[28:29], v[26:27]
	v_lshlrev_b32_e32 v28, 16, v82
	v_cvt_pk_bf16_f32 v17, v26, v27
	v_lshlrev_b32_e32 v26, 16, v18
	v_and_b32_e32 v27, 0xffff0000, v18
	v_and_b32_e32 v29, 0xffff0000, v82
	v_pk_mul_f32 v[26:27], v[28:29], v[26:27]
	v_lshlrev_b32_e32 v28, 16, v83
	v_cvt_pk_bf16_f32 v18, v26, v27
	v_lshlrev_b32_e32 v26, 16, v19
	v_and_b32_e32 v27, 0xffff0000, v19
	v_and_b32_e32 v29, 0xffff0000, v83
	v_pk_mul_f32 v[26:27], v[28:29], v[26:27]
	s_nop 0
	v_cvt_pk_bf16_f32 v19, v26, v27
	global_store_dwordx4 v[24:25], v[16:19], off sc1
	s_waitcnt lgkmcnt(0)
	s_nop 0
	v_lshlrev_b32_e32 v16, 16, v20
	v_and_b32_e32 v17, 0xffff0000, v20
	s_waitcnt vmcnt(6)
	v_lshlrev_b32_e32 v18, 16, v10
	v_and_b32_e32 v19, 0xffff0000, v10
	v_pk_mul_f32 v[16:17], v[18:19], v[16:17]
	v_lshlrev_b32_e32 v18, 16, v11
	v_cvt_pk_bf16_f32 v10, v16, v17
	v_lshlrev_b32_e32 v16, 16, v21
	v_and_b32_e32 v17, 0xffff0000, v21
	v_and_b32_e32 v19, 0xffff0000, v11
	v_pk_mul_f32 v[16:17], v[18:19], v[16:17]
	v_lshlrev_b32_e32 v18, 16, v12
	v_cvt_pk_bf16_f32 v11, v16, v17
	v_lshlrev_b32_e32 v16, 16, v22
	v_and_b32_e32 v17, 0xffff0000, v22
	v_and_b32_e32 v19, 0xffff0000, v12
	v_pk_mul_f32 v[16:17], v[18:19], v[16:17]
	v_lshlrev_b32_e32 v18, 16, v13
	v_cvt_pk_bf16_f32 v12, v16, v17
	v_lshlrev_b32_e32 v16, 16, v23
	v_and_b32_e32 v17, 0xffff0000, v23
	v_and_b32_e32 v19, 0xffff0000, v13
	v_pk_mul_f32 v[16:17], v[18:19], v[16:17]
	v_add_co_u32_e32 v20, vcc, s68, v24
	v_cvt_pk_bf16_f32 v13, v16, v17
	ds_read_b128 v[16:19], v0 offset:53248
	v_addc_co_u32_e32 v21, vcc, 0, v25, vcc
	global_store_dwordx4 v[20:21], v[10:13], off sc1
	ds_read_b128 v[10:13], v0 offset:54272
	s_waitcnt lgkmcnt(1)
	v_lshlrev_b32_e32 v20, 16, v16
	v_and_b32_e32 v21, 0xffff0000, v16
	s_waitcnt vmcnt(6)
	v_lshlrev_b32_e32 v22, 16, v6
	v_and_b32_e32 v23, 0xffff0000, v6
	v_pk_mul_f32 v[20:21], v[22:23], v[20:21]
	v_lshlrev_b32_e32 v16, 16, v17
	v_cvt_pk_bf16_f32 v6, v20, v21
	v_and_b32_e32 v17, 0xffff0000, v17
	v_lshlrev_b32_e32 v20, 16, v7
	v_and_b32_e32 v21, 0xffff0000, v7
	v_pk_mul_f32 v[16:17], v[20:21], v[16:17]
	v_lshlrev_b32_e32 v20, 16, v8
	v_cvt_pk_bf16_f32 v7, v16, v17
	v_lshlrev_b32_e32 v16, 16, v18
	v_and_b32_e32 v17, 0xffff0000, v18
	v_and_b32_e32 v21, 0xffff0000, v8
	v_pk_mul_f32 v[16:17], v[20:21], v[16:17]
	v_lshlrev_b32_e32 v18, 16, v9
	v_cvt_pk_bf16_f32 v8, v16, v17
	v_lshlrev_b32_e32 v16, 16, v19
	v_and_b32_e32 v17, 0xffff0000, v19
	v_and_b32_e32 v19, 0xffff0000, v9
	v_pk_mul_f32 v[16:17], v[18:19], v[16:17]
	s_nop 0
	v_cvt_pk_bf16_f32 v9, v16, v17
	v_add_co_u32_e32 v16, vcc, s70, v24
	s_nop 1
	v_addc_co_u32_e32 v17, vcc, 0, v25, vcc
	global_store_dwordx4 v[16:17], v[6:9], off sc1
	s_waitcnt lgkmcnt(0)
	s_nop 0
	v_lshlrev_b32_e32 v6, 16, v10
	v_and_b32_e32 v7, 0xffff0000, v10
	s_waitcnt vmcnt(6)
	v_lshlrev_b32_e32 v8, 16, v2
	v_and_b32_e32 v9, 0xffff0000, v2
	v_pk_mul_f32 v[6:7], v[8:9], v[6:7]
	v_lshlrev_b32_e32 v8, 16, v3
	v_cvt_pk_bf16_f32 v2, v6, v7
	v_lshlrev_b32_e32 v6, 16, v11
	v_and_b32_e32 v7, 0xffff0000, v11
	v_and_b32_e32 v9, 0xffff0000, v3
	v_pk_mul_f32 v[6:7], v[8:9], v[6:7]
	v_lshlrev_b32_e32 v8, 16, v4
	v_cvt_pk_bf16_f32 v3, v6, v7
	v_lshlrev_b32_e32 v6, 16, v12
	v_and_b32_e32 v7, 0xffff0000, v12
	v_and_b32_e32 v9, 0xffff0000, v4
	v_pk_mul_f32 v[6:7], v[8:9], v[6:7]
	v_lshlrev_b32_e32 v8, 16, v5
	v_cvt_pk_bf16_f32 v4, v6, v7
	v_lshlrev_b32_e32 v6, 16, v13
	v_and_b32_e32 v7, 0xffff0000, v13
	v_and_b32_e32 v9, 0xffff0000, v5
	v_pk_mul_f32 v[6:7], v[8:9], v[6:7]
	s_nop 0
	v_cvt_pk_bf16_f32 v5, v6, v7
	v_add_co_u32_e32 v6, vcc, 0xc000, v24
	s_nop 1
	v_addc_co_u32_e32 v7, vcc, 0, v25, vcc
	s_and_b64 vcc, exec, s[0:1]
	global_store_dwordx4 v[6:7], v[2:5], off sc1
	s_cbranch_vccnz .LBB0_544
	s_xor_b32 s20, s77, 1
	s_cmpk_gt_i32 s14, 0x3ff
	s_mov_b64 s[0:1], -1
	s_cbranch_scc1 .LBB0_661
	v_add_f32_e32 v0, v87, v15
	v_add_f32_e32 v2, v0, v92
	v_add_f32_e32 v6, v2, v91
	v_lshlrev_b32_e32 v5, 2, v206
	v_mov_b32_e32 v3, v6
	s_nop 1
	v_add_f32_dpp v3, v3, v3 row_shr:1 row_mask:0xf bank_mask:0xf
	s_nop 1
	v_add_f32_dpp v3, v3, v3 row_shr:2 row_mask:0xf bank_mask:0xf
	s_nop 1
	v_add_f32_dpp v3, v3, v3 row_shr:4 row_mask:0xf bank_mask:0xf
	s_nop 1
	v_add_f32_dpp v3, v3, v3 row_shr:8 row_mask:0xf bank_mask:0xf
	s_nop 1
	v_add_f32_dpp v3, v3, v3 row_bcast:15 row_mask:0xa bank_mask:0xf
	s_nop 1
	v_add_f32_dpp v3, v3, v3 row_bcast:31 row_mask:0xc bank_mask:0xf
	s_nop 0
	v_sub_f32_e32 v8, v3, v6
	v_xad_u32 v4, v5, -1, s15
	v_add_f32_e32 v5, v87, v8
	v_add_f32_e32 v3, v0, v8
	v_add_f32_e32 v0, v6, v8
	v_sub_f32_e32 v6, v5, v87
	v_cmp_ge_f32_e64 s[0:1], v6, -v197
	v_sub_f32_e32 v6, v3, v15
	v_add_f32_e32 v2, v2, v8
	v_cmp_lt_i32_e64 s[10:11], 0, v4
	v_cmp_ge_f32_e64 s[16:17], v6, -v197
	v_cmp_lt_i32_e64 s[12:13], -1, v4
	s_and_b64 s[16:17], s[10:11], s[16:17]
	s_bcnt1_i32_b64 s60, s[16:17]
	v_sub_f32_e32 v8, v2, v92
	s_and_b64 vcc, s[12:13], s[0:1]
	s_bcnt1_i32_b64 s61, vcc
	s_add_i32 s60, s60, s61
	v_cmp_lt_i32_e64 s[0:1], 1, v4
	v_cmp_ge_f32_e64 s[16:17], v8, -v197
	s_and_b64 s[16:17], s[0:1], s[16:17]
	s_bcnt1_i32_b64 s61, s[16:17]
	s_add_i32 s60, s60, s61
	v_sub_f32_e32 v9, v0, v91
	v_cmp_lt_i32_e32 vcc, 2, v4
	v_cmp_ge_f32_e64 s[16:17], v9, -v197
	s_and_b64 s[16:17], vcc, s[16:17]
	s_bcnt1_i32_b64 s61, s[16:17]
	s_add_i32 s60, s60, s61
	s_lshl_b32 s16, s20, 10
	s_add_i32 s56, s16, 0
	s_add_i32 s56, s56, 0x24800
	s_and_saveexec_b64 s[16:17], s[12:13]
	s_cbranch_execnz .LBB0_664
	s_or_b64 exec, exec, s[16:17]
	v_lshlrev_b32_e32 v4, 2, v4
	s_and_saveexec_b64 s[12:13], s[10:11]
	s_cbranch_execnz .LBB0_665

	.amdhsa_kernel _Z14fwd_megakernel4Args
		.amdhsa_group_segment_fixed_size 0
		.amdhsa_private_segment_fixed_size 0
		.amdhsa_kernarg_size 368
		.amdhsa_user_sgpr_count 2
		.amdhsa_user_sgpr_dispatch_ptr 0
		.amdhsa_user_sgpr_queue_ptr 0
		.amdhsa_user_sgpr_kernarg_segment_ptr 1
		.amdhsa_user_sgpr_dispatch_id 0
		.amdhsa_user_sgpr_kernarg_preload_length 0
		.amdhsa_user_sgpr_kernarg_preload_offset 0
		.amdhsa_user_sgpr_private_segment_size 0
		.amdhsa_uses_dynamic_stack 0
		.amdhsa_enable_private_segment 0
		.amdhsa_system_sgpr_workgroup_id_x 1
		.amdhsa_system_sgpr_workgroup_id_y 0
		.amdhsa_system_sgpr_workgroup_id_z 0
		.amdhsa_system_sgpr_workgroup_info 0
		.amdhsa_system_vgpr_workitem_id 2
		.amdhsa_next_free_vgpr 253
		.amdhsa_next_free_sgpr 100
		.amdhsa_accum_offset 256
		.amdhsa_reserve_vcc 1
		.amdhsa_float_round_mode_32 0
		.amdhsa_float_round_mode_16_64 0
		.amdhsa_float_denorm_mode_32 3
		.amdhsa_float_denorm_mode_16_64 3
		.amdhsa_dx10_clamp 1
		.amdhsa_ieee_mode 1
		.amdhsa_fp16_overflow 0
		.amdhsa_tg_split 0
		.amdhsa_exception_fp_ieee_invalid_op 0
		.amdhsa_exception_fp_denorm_src 0
		.amdhsa_exception_fp_ieee_div_zero 0
		.amdhsa_exception_fp_ieee_overflow 0
		.amdhsa_exception_fp_ieee_underflow 0
		.amdhsa_exception_fp_ieee_inexact 0
		.amdhsa_exception_int_div_zero 0
	.end_amdhsa_kernel

amdhsa.kernels:
  - .agpr_count:     0
    .args:
      - .offset:         0
        .size:           112
        .value_kind:     by_value
      - .offset:         112
        .size:           4
        .value_kind:     hidden_block_count_x
      - .offset:         116
        .size:           4
        .value_kind:     hidden_block_count_y
      - .offset:         120
        .size:           4
        .value_kind:     hidden_block_count_z
      - .offset:         124
        .size:           2
        .value_kind:     hidden_group_size_x
      - .offset:         126
        .size:           2
        .value_kind:     hidden_group_size_y
      - .offset:         128
        .size:           2
        .value_kind:     hidden_group_size_z
      - .offset:         130
        .size:           2
        .value_kind:     hidden_remainder_x
      - .offset:         132
        .size:           2
        .value_kind:     hidden_remainder_y
      - .offset:         134
        .size:           2
        .value_kind:     hidden_remainder_z
      - .offset:         152
        .size:           8
        .value_kind:     hidden_global_offset_x
      - .offset:         160
        .size:           8
        .value_kind:     hidden_global_offset_y
      - .offset:         168
        .size:           8
        .value_kind:     hidden_global_offset_z
      - .offset:         176
        .size:           2
        .value_kind:     hidden_grid_dims
      - .offset:         200
        .size:           8
        .value_kind:     hidden_multigrid_sync_arg
      - .offset:         232
        .size:           4
        .value_kind:     hidden_dynamic_lds_size
    .group_segment_fixed_size: 0
    .kernarg_segment_align: 8
    .kernarg_segment_size: 368
    .language:       OpenCL C
    .language_version:
      - 2
      - 0
    .max_flat_workgroup_size: 512
    .name:           _Z14fwd_megakernel4Args
    .private_segment_fixed_size: 0
    .sgpr_count:     106
    .sgpr_spill_count: 10
    .symbol:         _Z14fwd_megakernel4Args.kd
    .uniform_work_group_size: 1
    .uses_dynamic_stack: false
    .vgpr_count:     253
    .vgpr_spill_count: 0
    .wavefront_size: 64
